# attention pattern-2 merge epilogue: all partial (m,l)/O loads issued up front with counted waits
# speedup vs baseline: 1.0075x; 1.0006x over previous
; #define LAS __attribute__((address_space(3)))
; template <int NA, int MG>
; __device__ __forceinline__ void attn_pair_unit(const Params& p, int l, int u, LAS unsigned char* pl, int sub, int lane, int& g, const bool own0, const int nu) {
;     ...
;     { const int qr2 = lane >> 4;
; #pragma unroll 4
;       for (int t = 0; t < 8; ++t) {
;           const int rr = 4 * t + qr2;
;           int qrow2;
;           if (!NA) qrow2 = b * SEQ + (((lq + rr) << dsh) + z); else qrow2 = b * SEQ + (iq - (r >> 4) + (rr >> 4)) * 64 + (cq - (r & 15)) + (rr & 15);
;           u32x4 v = *(const LAS u32x4*)(sg + rr * 256 + (((lane & 15) ^ (rr & 15)) * 16));
;           if (MG) {
;               const f32x2 m3 = *(const LAS f32x2*)(sg + 8192 + rr * 8);
;               const float* mlp = (const float*)(p.ws + OFF_ML);
;               const f32x2 ma = *(const f32x2*)(mlp + (((size_t)qrow2) * 8 + head) * 2), mb = *(const f32x2*)(mlp + (((size_t)MTOK + qrow2) * 8 + head) * 2);
;               const bf16_t* part = (const bf16_t*)(p.ws + OFF_PART);
;               const u32x4 oa = *(const u32x4*)(part + (size_t)qrow2 * 1024 + head * 128 + (lane & 15) * 8);
;               const u32x4 ob = *(const u32x4*)(part + ((size_t)MTOK + qrow2) * 1024 + head * 128 + (lane & 15) * 8);
.LBB0_172:
	v_lshlrev_b32_e32 v10, s79, v6
	v_add_u32_e32 v26, s80, v10
	v_ashrrev_i32_e32 v27, 31, v26
	v_lshlrev_b64 v[14:15], 6, v[26:27]
	v_lshl_add_u64 v[14:15], s[52:53], 0, v[14:15]
	v_lshl_add_u64 v[18:19], v[26:27], 0, s[60:61]
	global_load_dwordx2 v[40:41], v[14:15], off
	v_lshlrev_b64 v[14:15], 6, v[18:19]
	v_lshl_add_u64 v[14:15], s[52:53], 0, v[14:15]
	global_load_dwordx2 v[42:43], v[14:15], off
	v_lshlrev_b64 v[18:19], 11, v[18:19]
	v_lshl_add_u64 v[18:19], v[4:5], 0, v[18:19]
	global_load_dwordx4 v[48:51], v[18:19], off
	v_lshlrev_b64 v[14:15], 11, v[26:27]
	v_lshl_add_u64 v[14:15], v[4:5], 0, v[14:15]
	global_load_dwordx4 v[44:47], v[14:15], off
	v_add_lshl_u32 v10, v6, 4, s79
	v_add_u32_e32 v26, s80, v10
	v_ashrrev_i32_e32 v27, 31, v26
	v_lshlrev_b64 v[14:15], 6, v[26:27]
	v_lshl_add_u64 v[14:15], s[52:53], 0, v[14:15]
	v_lshl_add_u64 v[18:19], v[26:27], 0, s[60:61]
	global_load_dwordx2 v[52:53], v[14:15], off
	v_lshlrev_b64 v[14:15], 6, v[18:19]
	v_lshl_add_u64 v[14:15], s[52:53], 0, v[14:15]
	global_load_dwordx2 v[54:55], v[14:15], off
	v_lshlrev_b64 v[18:19], 11, v[18:19]
	v_lshl_add_u64 v[18:19], v[4:5], 0, v[18:19]
	global_load_dwordx4 v[60:63], v[18:19], off
	v_lshlrev_b64 v[14:15], 11, v[26:27]
	v_lshl_add_u64 v[14:15], v[4:5], 0, v[14:15]
	global_load_dwordx4 v[56:59], v[14:15], off
	v_add_lshl_u32 v10, v6, 8, s79
	v_add_u32_e32 v26, s80, v10
	v_ashrrev_i32_e32 v27, 31, v26
	v_lshlrev_b64 v[14:15], 6, v[26:27]
	v_lshl_add_u64 v[14:15], s[52:53], 0, v[14:15]
	v_lshl_add_u64 v[18:19], v[26:27], 0, s[60:61]
	global_load_dwordx2 v[64:65], v[14:15], off
	v_lshlrev_b64 v[14:15], 6, v[18:19]
	v_lshl_add_u64 v[14:15], s[52:53], 0, v[14:15]
	global_load_dwordx2 v[66:67], v[14:15], off
	v_lshlrev_b64 v[18:19], 11, v[18:19]
	v_lshl_add_u64 v[18:19], v[4:5], 0, v[18:19]
	global_load_dwordx4 v[72:75], v[18:19], off
	v_lshlrev_b64 v[14:15], 11, v[26:27]
	v_lshl_add_u64 v[14:15], v[4:5], 0, v[14:15]
	global_load_dwordx4 v[68:71], v[14:15], off
	v_add_lshl_u32 v10, v6, 12, s79
	v_add_u32_e32 v26, s80, v10
	v_ashrrev_i32_e32 v27, 31, v26
	v_lshlrev_b64 v[14:15], 6, v[26:27]
	v_lshl_add_u64 v[14:15], s[52:53], 0, v[14:15]
	v_lshl_add_u64 v[18:19], v[26:27], 0, s[60:61]
	global_load_dwordx2 v[76:77], v[14:15], off
	v_lshlrev_b64 v[14:15], 6, v[18:19]
	v_lshl_add_u64 v[14:15], s[52:53], 0, v[14:15]
	global_load_dwordx2 v[78:79], v[14:15], off
	v_lshlrev_b64 v[18:19], 11, v[18:19]
	v_lshl_add_u64 v[18:19], v[4:5], 0, v[18:19]
	global_load_dwordx4 v[84:87], v[18:19], off
	v_lshlrev_b64 v[14:15], 11, v[26:27]
	v_lshl_add_u64 v[14:15], v[4:5], 0, v[14:15]
	global_load_dwordx4 v[80:83], v[14:15], off
	v_add_lshl_u32 v10, v6, 16, s79
	v_add_u32_e32 v26, s80, v10
	v_ashrrev_i32_e32 v27, 31, v26
	v_lshlrev_b64 v[14:15], 6, v[26:27]
	v_lshl_add_u64 v[14:15], s[52:53], 0, v[14:15]
	v_lshl_add_u64 v[18:19], v[26:27], 0, s[60:61]
	global_load_dwordx2 v[88:89], v[14:15], off
	v_lshlrev_b64 v[14:15], 6, v[18:19]
	v_lshl_add_u64 v[14:15], s[52:53], 0, v[14:15]
	global_load_dwordx2 v[90:91], v[14:15], off
	v_lshlrev_b64 v[18:19], 11, v[18:19]
	v_lshl_add_u64 v[18:19], v[4:5], 0, v[18:19]
	global_load_dwordx4 v[96:99], v[18:19], off
	v_lshlrev_b64 v[14:15], 11, v[26:27]
	v_lshl_add_u64 v[14:15], v[4:5], 0, v[14:15]
	global_load_dwordx4 v[92:95], v[14:15], off
	v_add_lshl_u32 v10, v6, 20, s79
	v_add_u32_e32 v26, s80, v10
	v_ashrrev_i32_e32 v27, 31, v26
	v_lshlrev_b64 v[14:15], 6, v[26:27]
	v_lshl_add_u64 v[14:15], s[52:53], 0, v[14:15]
	v_lshl_add_u64 v[18:19], v[26:27], 0, s[60:61]
	global_load_dwordx2 v[100:101], v[14:15], off
	v_lshlrev_b64 v[14:15], 6, v[18:19]
	v_lshl_add_u64 v[14:15], s[52:53], 0, v[14:15]
	global_load_dwordx2 v[102:103], v[14:15], off
	v_lshlrev_b64 v[18:19], 11, v[18:19]
	v_lshl_add_u64 v[18:19], v[4:5], 0, v[18:19]
	global_load_dwordx4 v[108:111], v[18:19], off
	v_lshlrev_b64 v[14:15], 11, v[26:27]
	v_lshl_add_u64 v[14:15], v[4:5], 0, v[14:15]
	global_load_dwordx4 v[104:107], v[14:15], off
	v_add_lshl_u32 v10, v6, 24, s79
	v_add_u32_e32 v26, s80, v10
	v_ashrrev_i32_e32 v27, 31, v26
	v_lshlrev_b64 v[14:15], 6, v[26:27]
	v_lshl_add_u64 v[14:15], s[52:53], 0, v[14:15]
	v_lshl_add_u64 v[18:19], v[26:27], 0, s[60:61]
	global_load_dwordx2 v[184:185], v[14:15], off
	v_lshlrev_b64 v[14:15], 6, v[18:19]
	v_lshl_add_u64 v[14:15], s[52:53], 0, v[14:15]
	global_load_dwordx2 v[186:187], v[14:15], off
	v_lshlrev_b64 v[18:19], 11, v[18:19]
	v_lshl_add_u64 v[18:19], v[4:5], 0, v[18:19]
	global_load_dwordx4 v[192:195], v[18:19], off
	v_lshlrev_b64 v[14:15], 11, v[26:27]
	v_lshl_add_u64 v[14:15], v[4:5], 0, v[14:15]
	global_load_dwordx4 v[188:191], v[14:15], off
	v_add_lshl_u32 v10, v6, 28, s79
	v_add_u32_e32 v26, s80, v10
	v_ashrrev_i32_e32 v27, 31, v26
	v_lshlrev_b64 v[14:15], 6, v[26:27]
	v_lshl_add_u64 v[14:15], s[52:53], 0, v[14:15]
	v_lshl_add_u64 v[18:19], v[26:27], 0, s[60:61]
	global_load_dwordx2 v[140:141], v[14:15], off
	v_lshlrev_b64 v[14:15], 6, v[18:19]
	v_lshl_add_u64 v[14:15], s[52:53], 0, v[14:15]
	global_load_dwordx2 v[142:143], v[14:15], off
	v_lshlrev_b64 v[18:19], 11, v[18:19]
	v_lshl_add_u64 v[18:19], v[4:5], 0, v[18:19]
	global_load_dwordx4 v[214:217], v[18:19], off
	v_lshlrev_b64 v[14:15], 11, v[26:27]
	v_lshl_add_u64 v[14:15], v[4:5], 0, v[14:15]
	global_load_dwordx4 v[210:213], v[14:15], off
	v_add_u32_e32 v39, s2, v136
	v_xor_b32_e32 v10, v115, v159
	v_lshlrev_b32_e32 v10, 4, v10
	v_and_b32_e32 v10, 0xf0, v10
	v_add3_u32 v10, s2, v10, v137
	ds_read_b64 v[22:23], v39
	ds_read_b128 v[10:13], v10
	v_lshlrev_b32_e32 v26, s79, v6
	v_add_u32_e32 v26, s80, v26
	v_ashrrev_i32_e32 v27, 31, v26
	s_waitcnt vmcnt(28)
; #define LAS __attribute__((address_space(3)))
; __device__ __forceinline__ unsigned pk2(float lo, float hi) { f32x2 v = {lo, hi}; return __builtin_bit_cast(unsigned, __builtin_convertvector(v, bf16x2_t)); }
; __device__ __forceinline__ float bf_lo(unsigned w) { return __uint_as_float(w << 16); }
; __device__ __forceinline__ float bf_hi(unsigned w) { return __uint_as_float(w & 0xffff0000u); }
; template <int NA, int MG>
; __device__ __forceinline__ void attn_pair_unit(const Params& p, int l, int u, LAS unsigned char* pl, int sub, int lane, int& g, const bool own0, const int nu) {
;     ...
;           const int rr = 4 * t + qr2;
;           int qrow2;
;           if (!NA) qrow2 = b * SEQ + (((lq + rr) << dsh) + z); else qrow2 = b * SEQ + (iq - (r >> 4) + (rr >> 4)) * 64 + (cq - (r & 15)) + (rr & 15);
;           u32x4 v = *(const LAS u32x4*)(sg + rr * 256 + (((lane & 15) ^ (rr & 15)) * 16));
;           if (MG) {
;               const f32x2 m3 = *(const LAS f32x2*)(sg + 8192 + rr * 8);
;               const float* mlp = (const float*)(p.ws + OFF_ML);
;               const f32x2 ma = *(const f32x2*)(mlp + (((size_t)qrow2) * 8 + head) * 2), mb = *(const f32x2*)(mlp + (((size_t)MTOK + qrow2) * 8 + head) * 2);
;               const bf16_t* part = (const bf16_t*)(p.ws + OFF_PART);
;               const u32x4 oa = *(const u32x4*)(part + (size_t)qrow2 * 1024 + head * 128 + (lane & 15) * 8);
;               const u32x4 ob = *(const u32x4*)(part + ((size_t)MTOK + qrow2) * 1024 + head * 128 + (lane & 15) * 8);
;               const float mm = fmaxf(ma[0], fmaxf(mb[0], m3[0]));
;               const float wa = ma[1] * __builtin_amdgcn_exp2f(ma[0] - mm), wb = mb[1] * __builtin_amdgcn_exp2f(mb[0] - mm), w3 = m3[1] * __builtin_amdgcn_exp2f(m3[0] - mm);
;               const float winv = 1.0f / (wa + wb + w3);
; #pragma unroll
;               for (int e = 0; e < 4; ++e) {
;                   const float lo = (wa * bf_lo(oa[e]) + wb * bf_lo(ob[e]) + w3 * bf_lo(v[e])) * winv;
;                   const float hi = (wa * bf_hi(oa[e]) + wb * bf_hi(ob[e]) + w3 * bf_hi(v[e])) * winv;
;                   v[e] = pk2(lo, hi);
;               }
;           }
;           *(u32x4*)(dst + (size_t)qrow2 * dpitch + (lane & 15) * 8) = v;
	v_mov_b32_e32 v28, v40
	v_mov_b32_e32 v29, v41
	v_mov_b32_e32 v30, v42
	v_mov_b32_e32 v31, v43
	v_mov_b32_e32 v18, v48
	v_mov_b32_e32 v19, v49
	v_mov_b32_e32 v20, v50
	v_mov_b32_e32 v21, v51
	v_mov_b32_e32 v14, v44
	v_mov_b32_e32 v15, v45
	v_mov_b32_e32 v16, v46
	v_mov_b32_e32 v17, v47
	s_waitcnt lgkmcnt(0)
	v_lshlrev_b32_e32 v36, 16, v10
	v_and_b32_e32 v37, 0xffff0000, v10
	v_max3_f32 v34, v28, v30, v22
	v_sub_f32_e32 v28, v28, v34
	v_exp_f32_e32 v33, v28
	v_sub_f32_e32 v28, v30, v34
	v_exp_f32_e32 v32, v28
	v_sub_f32_e32 v22, v22, v34
	v_exp_f32_e32 v30, v22
	v_mov_b32_e32 v28, v31
	v_pk_mul_f32 v[28:29], v[28:29], v[32:33]
	v_and_b32_e32 v35, 0xffff0000, v18
	v_add_f32_e32 v31, v29, v28
	v_fmac_f32_e32 v31, v23, v30
	v_mul_f32_e32 v22, v23, v30
	v_div_scale_f32 v23, s[40:41], v31, v31, 1.0
	v_rcp_f32_e32 v30, v23
	s_nop 0
	v_fma_f32 v32, -v23, v30, 1.0
	v_fmac_f32_e32 v30, v32, v30
	v_div_scale_f32 v32, vcc, 1.0, v31, 1.0
	v_mul_f32_e32 v33, v32, v30
	v_fma_f32 v34, -v23, v33, v32
	v_fmac_f32_e32 v33, v34, v30
	v_fma_f32 v23, -v23, v33, v32
	v_lshlrev_b32_e32 v34, 16, v14
	v_div_fmas_f32 v23, v23, v30, v33
	v_lshlrev_b32_e32 v32, 16, v18
	v_and_b32_e32 v33, 0xffff0000, v14
	v_pk_mul_f32 v[34:35], v[28:29], v[34:35] op_sel:[1,0] op_sel_hi:[0,1]
	v_pk_fma_f32 v[32:33], v[28:29], v[32:33], v[34:35]
	v_div_fixup_f32 v30, v23, v31, 1.0
	v_pk_fma_f32 v[32:33], v[22:23], v[36:37], v[32:33] op_sel_hi:[0,1,1]
	v_pk_mul_f32 v[32:33], v[30:31], v[32:33] op_sel_hi:[0,1]
	v_cvt_pk_bf16_f32 v10, v32, v33
	v_and_b32_e32 v33, 0xffff0000, v15
	v_lshlrev_b32_e32 v14, 16, v15
	v_and_b32_e32 v15, 0xffff0000, v19
	v_lshlrev_b32_e32 v32, 16, v19
	v_pk_mul_f32 v[14:15], v[28:29], v[14:15] op_sel:[1,0] op_sel_hi:[0,1]
	v_lshlrev_b32_e32 v18, 16, v11
	v_and_b32_e32 v19, 0xffff0000, v11
	v_pk_fma_f32 v[14:15], v[28:29], v[32:33], v[14:15]
	v_lshlrev_b32_e32 v32, 16, v12
	v_pk_fma_f32 v[14:15], v[22:23], v[18:19], v[14:15] op_sel_hi:[0,1,1]
	v_pk_mul_f32 v[14:15], v[30:31], v[14:15] op_sel_hi:[0,1]
	v_lshlrev_b32_e32 v18, 16, v16
	v_and_b32_e32 v19, 0xffff0000, v20
	v_cvt_pk_bf16_f32 v11, v14, v15
	v_lshlrev_b32_e32 v14, 16, v20
	v_and_b32_e32 v15, 0xffff0000, v16
	v_pk_mul_f32 v[18:19], v[28:29], v[18:19] op_sel:[1,0] op_sel_hi:[0,1]
	v_and_b32_e32 v33, 0xffff0000, v12
	v_pk_fma_f32 v[14:15], v[28:29], v[14:15], v[18:19]
	v_lshlrev_b32_e32 v16, 16, v17
	v_pk_fma_f32 v[14:15], v[22:23], v[32:33], v[14:15] op_sel_hi:[0,1,1]
	v_pk_mul_f32 v[14:15], v[30:31], v[14:15] op_sel_hi:[0,1]
	v_cvt_pk_bf16_f32 v12, v14, v15
	v_and_b32_e32 v15, 0xffff0000, v17
	v_and_b32_e32 v17, 0xffff0000, v21
	v_lshlrev_b32_e32 v14, 16, v21
	v_pk_mul_f32 v[16:17], v[28:29], v[16:17] op_sel:[1,0] op_sel_hi:[0,1]
	v_pk_fma_f32 v[14:15], v[28:29], v[14:15], v[16:17]
	v_lshlrev_b32_e32 v16, 16, v13
	v_and_b32_e32 v17, 0xffff0000, v13
	v_pk_fma_f32 v[14:15], v[22:23], v[16:17], v[14:15] op_sel_hi:[0,1,1]
	v_pk_mul_f32 v[14:15], v[30:31], v[14:15] op_sel_hi:[0,1]
	v_cvt_pk_bf16_f32 v13, v14, v15
	v_lshlrev_b64 v[14:15], 12, v[26:27]
	v_lshl_add_u64 v[14:15], v[2:3], 0, v[14:15]
	global_store_dwordx4 v[14:15], v[10:13], off
	s_nop 1
	v_add_u32_e32 v10, 4, v115
	v_xor_b32_e32 v10, v10, v159
	v_lshlrev_b32_e32 v10, 4, v10
	v_and_b32_e32 v10, 0xf0, v10
	v_add3_u32 v10, s2, v10, v137
	ds_read_b64 v[22:23], v39 offset:32
	ds_read_b128 v[10:13], v10 offset:1024
	v_add_lshl_u32 v26, v6, 4, s79
	v_add_u32_e32 v26, s80, v26
	v_ashrrev_i32_e32 v27, 31, v26
	s_waitcnt vmcnt(25)
	v_mov_b32_e32 v28, v52
	v_mov_b32_e32 v29, v53
	v_mov_b32_e32 v30, v54
	v_mov_b32_e32 v31, v55
	v_mov_b32_e32 v18, v60
	v_mov_b32_e32 v19, v61
	v_mov_b32_e32 v20, v62
	v_mov_b32_e32 v21, v63
	v_mov_b32_e32 v14, v56
	v_mov_b32_e32 v15, v57
	v_mov_b32_e32 v16, v58
	v_mov_b32_e32 v17, v59
	s_waitcnt lgkmcnt(0)
	v_lshlrev_b32_e32 v36, 16, v10
	v_and_b32_e32 v37, 0xffff0000, v10
	v_max3_f32 v34, v28, v30, v22
	v_sub_f32_e32 v28, v28, v34
	v_exp_f32_e32 v33, v28
	v_sub_f32_e32 v28, v30, v34
	v_exp_f32_e32 v32, v28
	v_sub_f32_e32 v22, v22, v34
	v_exp_f32_e32 v30, v22
	v_mov_b32_e32 v28, v31
	v_pk_mul_f32 v[28:29], v[28:29], v[32:33]
	v_and_b32_e32 v35, 0xffff0000, v18
	v_add_f32_e32 v31, v29, v28
	v_fmac_f32_e32 v31, v23, v30
	v_mul_f32_e32 v22, v23, v30
	v_div_scale_f32 v23, s[40:41], v31, v31, 1.0
	v_rcp_f32_e32 v30, v23
	s_nop 0
	v_fma_f32 v32, -v23, v30, 1.0
	v_fmac_f32_e32 v30, v32, v30
	v_div_scale_f32 v32, vcc, 1.0, v31, 1.0
	v_mul_f32_e32 v33, v32, v30
	v_fma_f32 v34, -v23, v33, v32
	v_fmac_f32_e32 v33, v34, v30
	v_fma_f32 v23, -v23, v33, v32
	v_lshlrev_b32_e32 v34, 16, v14
	v_div_fmas_f32 v23, v23, v30, v33
	v_lshlrev_b32_e32 v32, 16, v18
	v_and_b32_e32 v33, 0xffff0000, v14
	v_pk_mul_f32 v[34:35], v[28:29], v[34:35] op_sel:[1,0] op_sel_hi:[0,1]
	v_pk_fma_f32 v[32:33], v[28:29], v[32:33], v[34:35]
	v_div_fixup_f32 v30, v23, v31, 1.0
	v_pk_fma_f32 v[32:33], v[22:23], v[36:37], v[32:33] op_sel_hi:[0,1,1]
	v_pk_mul_f32 v[32:33], v[30:31], v[32:33] op_sel_hi:[0,1]
	v_cvt_pk_bf16_f32 v10, v32, v33
	v_and_b32_e32 v33, 0xffff0000, v15
	v_lshlrev_b32_e32 v14, 16, v15
	v_and_b32_e32 v15, 0xffff0000, v19
	v_lshlrev_b32_e32 v32, 16, v19
	v_pk_mul_f32 v[14:15], v[28:29], v[14:15] op_sel:[1,0] op_sel_hi:[0,1]
	v_lshlrev_b32_e32 v18, 16, v11
	v_and_b32_e32 v19, 0xffff0000, v11
	v_pk_fma_f32 v[14:15], v[28:29], v[32:33], v[14:15]
	v_lshlrev_b32_e32 v32, 16, v12
	v_pk_fma_f32 v[14:15], v[22:23], v[18:19], v[14:15] op_sel_hi:[0,1,1]
	v_pk_mul_f32 v[14:15], v[30:31], v[14:15] op_sel_hi:[0,1]
	v_lshlrev_b32_e32 v18, 16, v16
	v_and_b32_e32 v19, 0xffff0000, v20
	v_cvt_pk_bf16_f32 v11, v14, v15
	v_lshlrev_b32_e32 v14, 16, v20
	v_and_b32_e32 v15, 0xffff0000, v16
	v_pk_mul_f32 v[18:19], v[28:29], v[18:19] op_sel:[1,0] op_sel_hi:[0,1]
	v_and_b32_e32 v33, 0xffff0000, v12
	v_pk_fma_f32 v[14:15], v[28:29], v[14:15], v[18:19]
	v_lshlrev_b32_e32 v16, 16, v17
	v_pk_fma_f32 v[14:15], v[22:23], v[32:33], v[14:15] op_sel_hi:[0,1,1]
	v_pk_mul_f32 v[14:15], v[30:31], v[14:15] op_sel_hi:[0,1]
	v_cvt_pk_bf16_f32 v12, v14, v15
	v_and_b32_e32 v15, 0xffff0000, v17
	v_and_b32_e32 v17, 0xffff0000, v21
	v_lshlrev_b32_e32 v14, 16, v21
	v_pk_mul_f32 v[16:17], v[28:29], v[16:17] op_sel:[1,0] op_sel_hi:[0,1]
	v_pk_fma_f32 v[14:15], v[28:29], v[14:15], v[16:17]
	v_lshlrev_b32_e32 v16, 16, v13
	v_and_b32_e32 v17, 0xffff0000, v13
	v_pk_fma_f32 v[14:15], v[22:23], v[16:17], v[14:15] op_sel_hi:[0,1,1]
	v_pk_mul_f32 v[14:15], v[30:31], v[14:15] op_sel_hi:[0,1]
	v_cvt_pk_bf16_f32 v13, v14, v15
	v_lshlrev_b64 v[14:15], 12, v[26:27]
	v_lshl_add_u64 v[14:15], v[2:3], 0, v[14:15]
	global_store_dwordx4 v[14:15], v[10:13], off
	s_nop 1
	v_add_u32_e32 v10, 8, v115
	v_xor_b32_e32 v10, v10, v159
	v_lshlrev_b32_e32 v10, 4, v10
	v_and_b32_e32 v10, 0xf0, v10
	v_add3_u32 v10, s2, v10, v137
	ds_read_b64 v[22:23], v39 offset:64
	ds_read_b128 v[10:13], v10 offset:2048
	v_add_lshl_u32 v26, v6, 8, s79
	v_add_u32_e32 v26, s80, v26
	v_ashrrev_i32_e32 v27, 31, v26
	s_waitcnt vmcnt(22)
; #define LAS __attribute__((address_space(3)))
; __device__ __forceinline__ unsigned pk2(float lo, float hi) { f32x2 v = {lo, hi}; return __builtin_bit_cast(unsigned, __builtin_convertvector(v, bf16x2_t)); }
; __device__ __forceinline__ float bf_lo(unsigned w) { return __uint_as_float(w << 16); }
; __device__ __forceinline__ float bf_hi(unsigned w) { return __uint_as_float(w & 0xffff0000u); }
; template <int NA, int MG>
; __device__ __forceinline__ void attn_pair_unit(const Params& p, int l, int u, LAS unsigned char* pl, int sub, int lane, int& g, const bool own0, const int nu) {
;     ...
;           const int rr = 4 * t + qr2;
;           int qrow2;
;           if (!NA) qrow2 = b * SEQ + (((lq + rr) << dsh) + z); else qrow2 = b * SEQ + (iq - (r >> 4) + (rr >> 4)) * 64 + (cq - (r & 15)) + (rr & 15);
;           u32x4 v = *(const LAS u32x4*)(sg + rr * 256 + (((lane & 15) ^ (rr & 15)) * 16));
;           if (MG) {
;               const f32x2 m3 = *(const LAS f32x2*)(sg + 8192 + rr * 8);
;               const float* mlp = (const float*)(p.ws + OFF_ML);
;               const f32x2 ma = *(const f32x2*)(mlp + (((size_t)qrow2) * 8 + head) * 2), mb = *(const f32x2*)(mlp + (((size_t)MTOK + qrow2) * 8 + head) * 2);
;               const bf16_t* part = (const bf16_t*)(p.ws + OFF_PART);
;               const u32x4 oa = *(const u32x4*)(part + (size_t)qrow2 * 1024 + head * 128 + (lane & 15) * 8);
;               const u32x4 ob = *(const u32x4*)(part + ((size_t)MTOK + qrow2) * 1024 + head * 128 + (lane & 15) * 8);
;               const float mm = fmaxf(ma[0], fmaxf(mb[0], m3[0]));
;               const float wa = ma[1] * __builtin_amdgcn_exp2f(ma[0] - mm), wb = mb[1] * __builtin_amdgcn_exp2f(mb[0] - mm), w3 = m3[1] * __builtin_amdgcn_exp2f(m3[0] - mm);
;               const float winv = 1.0f / (wa + wb + w3);
; #pragma unroll
;               for (int e = 0; e < 4; ++e) {
;                   const float lo = (wa * bf_lo(oa[e]) + wb * bf_lo(ob[e]) + w3 * bf_lo(v[e])) * winv;
;                   const float hi = (wa * bf_hi(oa[e]) + wb * bf_hi(ob[e]) + w3 * bf_hi(v[e])) * winv;
;                   v[e] = pk2(lo, hi);
;               }
;           }
;           *(u32x4*)(dst + (size_t)qrow2 * dpitch + (lane & 15) * 8) = v;
	v_mov_b32_e32 v28, v64
	v_mov_b32_e32 v29, v65
	v_mov_b32_e32 v30, v66
	v_mov_b32_e32 v31, v67
	v_mov_b32_e32 v18, v72
	v_mov_b32_e32 v19, v73
	v_mov_b32_e32 v20, v74
	v_mov_b32_e32 v21, v75
	v_mov_b32_e32 v14, v68
	v_mov_b32_e32 v15, v69
	v_mov_b32_e32 v16, v70
	v_mov_b32_e32 v17, v71
	s_waitcnt lgkmcnt(0)
	v_lshlrev_b32_e32 v36, 16, v10
	v_and_b32_e32 v37, 0xffff0000, v10
	v_max3_f32 v34, v28, v30, v22
	v_sub_f32_e32 v28, v28, v34
	v_exp_f32_e32 v33, v28
	v_sub_f32_e32 v28, v30, v34
	v_exp_f32_e32 v32, v28
	v_sub_f32_e32 v22, v22, v34
	v_exp_f32_e32 v30, v22
	v_mov_b32_e32 v28, v31
	v_pk_mul_f32 v[28:29], v[28:29], v[32:33]
	v_and_b32_e32 v35, 0xffff0000, v18
	v_add_f32_e32 v31, v29, v28
	v_fmac_f32_e32 v31, v23, v30
	v_mul_f32_e32 v22, v23, v30
	v_div_scale_f32 v23, s[40:41], v31, v31, 1.0
	v_rcp_f32_e32 v30, v23
	s_nop 0
	v_fma_f32 v32, -v23, v30, 1.0
	v_fmac_f32_e32 v30, v32, v30
	v_div_scale_f32 v32, vcc, 1.0, v31, 1.0
	v_mul_f32_e32 v33, v32, v30
	v_fma_f32 v34, -v23, v33, v32
	v_fmac_f32_e32 v33, v34, v30
	v_fma_f32 v23, -v23, v33, v32
	v_lshlrev_b32_e32 v34, 16, v14
	v_div_fmas_f32 v23, v23, v30, v33
	v_lshlrev_b32_e32 v32, 16, v18
	v_and_b32_e32 v33, 0xffff0000, v14
	v_pk_mul_f32 v[34:35], v[28:29], v[34:35] op_sel:[1,0] op_sel_hi:[0,1]
	v_pk_fma_f32 v[32:33], v[28:29], v[32:33], v[34:35]
	v_div_fixup_f32 v30, v23, v31, 1.0
	v_pk_fma_f32 v[32:33], v[22:23], v[36:37], v[32:33] op_sel_hi:[0,1,1]
	v_pk_mul_f32 v[32:33], v[30:31], v[32:33] op_sel_hi:[0,1]
	v_cvt_pk_bf16_f32 v10, v32, v33
	v_and_b32_e32 v33, 0xffff0000, v15
	v_lshlrev_b32_e32 v14, 16, v15
	v_and_b32_e32 v15, 0xffff0000, v19
	v_lshlrev_b32_e32 v32, 16, v19
	v_pk_mul_f32 v[14:15], v[28:29], v[14:15] op_sel:[1,0] op_sel_hi:[0,1]
	v_lshlrev_b32_e32 v18, 16, v11
	v_and_b32_e32 v19, 0xffff0000, v11
	v_pk_fma_f32 v[14:15], v[28:29], v[32:33], v[14:15]
	v_lshlrev_b32_e32 v32, 16, v12
	v_pk_fma_f32 v[14:15], v[22:23], v[18:19], v[14:15] op_sel_hi:[0,1,1]
	v_pk_mul_f32 v[14:15], v[30:31], v[14:15] op_sel_hi:[0,1]
	v_lshlrev_b32_e32 v18, 16, v16
	v_and_b32_e32 v19, 0xffff0000, v20
	v_cvt_pk_bf16_f32 v11, v14, v15
	v_lshlrev_b32_e32 v14, 16, v20
	v_and_b32_e32 v15, 0xffff0000, v16
	v_pk_mul_f32 v[18:19], v[28:29], v[18:19] op_sel:[1,0] op_sel_hi:[0,1]
	v_and_b32_e32 v33, 0xffff0000, v12
	v_pk_fma_f32 v[14:15], v[28:29], v[14:15], v[18:19]
	v_lshlrev_b32_e32 v16, 16, v17
	v_pk_fma_f32 v[14:15], v[22:23], v[32:33], v[14:15] op_sel_hi:[0,1,1]
	v_pk_mul_f32 v[14:15], v[30:31], v[14:15] op_sel_hi:[0,1]
	v_cvt_pk_bf16_f32 v12, v14, v15
	v_and_b32_e32 v15, 0xffff0000, v17
	v_and_b32_e32 v17, 0xffff0000, v21
	v_lshlrev_b32_e32 v14, 16, v21
	v_pk_mul_f32 v[16:17], v[28:29], v[16:17] op_sel:[1,0] op_sel_hi:[0,1]
	v_pk_fma_f32 v[14:15], v[28:29], v[14:15], v[16:17]
	v_lshlrev_b32_e32 v16, 16, v13
	v_and_b32_e32 v17, 0xffff0000, v13
	v_pk_fma_f32 v[14:15], v[22:23], v[16:17], v[14:15] op_sel_hi:[0,1,1]
	v_pk_mul_f32 v[14:15], v[30:31], v[14:15] op_sel_hi:[0,1]
	v_cvt_pk_bf16_f32 v13, v14, v15
	v_lshlrev_b64 v[14:15], 12, v[26:27]
	v_lshl_add_u64 v[14:15], v[2:3], 0, v[14:15]
	global_store_dwordx4 v[14:15], v[10:13], off
	s_nop 1
	v_add_u32_e32 v10, 12, v115
	v_xor_b32_e32 v10, v10, v159
	v_lshlrev_b32_e32 v10, 4, v10
	v_and_b32_e32 v10, 0xf0, v10
	v_add3_u32 v10, s2, v10, v137
	ds_read_b64 v[22:23], v39 offset:96
	ds_read_b128 v[10:13], v10 offset:3072
	v_add_lshl_u32 v26, v6, 12, s79
	v_add_u32_e32 v26, s80, v26
	v_ashrrev_i32_e32 v27, 31, v26
	s_waitcnt vmcnt(19)
	v_mov_b32_e32 v28, v76
	v_mov_b32_e32 v29, v77
	v_mov_b32_e32 v30, v78
	v_mov_b32_e32 v31, v79
	v_mov_b32_e32 v18, v84
	v_mov_b32_e32 v19, v85
	v_mov_b32_e32 v20, v86
	v_mov_b32_e32 v21, v87
	v_mov_b32_e32 v14, v80
	v_mov_b32_e32 v15, v81
	v_mov_b32_e32 v16, v82
	v_mov_b32_e32 v17, v83
	s_waitcnt lgkmcnt(0)
	v_lshlrev_b32_e32 v36, 16, v10
	v_and_b32_e32 v37, 0xffff0000, v10
	v_max3_f32 v34, v28, v30, v22
	v_sub_f32_e32 v28, v28, v34
	v_exp_f32_e32 v33, v28
	v_sub_f32_e32 v28, v30, v34
	v_exp_f32_e32 v32, v28
	v_sub_f32_e32 v22, v22, v34
	v_exp_f32_e32 v30, v22
	v_mov_b32_e32 v28, v31
	v_pk_mul_f32 v[28:29], v[28:29], v[32:33]
	v_and_b32_e32 v35, 0xffff0000, v18
	v_add_f32_e32 v31, v29, v28
	v_fmac_f32_e32 v31, v23, v30
	v_mul_f32_e32 v22, v23, v30
	v_div_scale_f32 v23, s[40:41], v31, v31, 1.0
	v_rcp_f32_e32 v30, v23
	s_nop 0
	v_fma_f32 v32, -v23, v30, 1.0
	v_fmac_f32_e32 v30, v32, v30
	v_div_scale_f32 v32, vcc, 1.0, v31, 1.0
	v_mul_f32_e32 v33, v32, v30
	v_fma_f32 v34, -v23, v33, v32
	v_fmac_f32_e32 v33, v34, v30
	v_fma_f32 v23, -v23, v33, v32
	v_lshlrev_b32_e32 v34, 16, v14
	v_div_fmas_f32 v23, v23, v30, v33
	v_lshlrev_b32_e32 v32, 16, v18
	v_and_b32_e32 v33, 0xffff0000, v14
	v_pk_mul_f32 v[34:35], v[28:29], v[34:35] op_sel:[1,0] op_sel_hi:[0,1]
	v_pk_fma_f32 v[32:33], v[28:29], v[32:33], v[34:35]
	v_div_fixup_f32 v30, v23, v31, 1.0
	v_pk_fma_f32 v[32:33], v[22:23], v[36:37], v[32:33] op_sel_hi:[0,1,1]
	v_pk_mul_f32 v[32:33], v[30:31], v[32:33] op_sel_hi:[0,1]
	v_cvt_pk_bf16_f32 v10, v32, v33
	v_and_b32_e32 v33, 0xffff0000, v15
	v_lshlrev_b32_e32 v14, 16, v15
	v_and_b32_e32 v15, 0xffff0000, v19
	v_lshlrev_b32_e32 v32, 16, v19
	v_pk_mul_f32 v[14:15], v[28:29], v[14:15] op_sel:[1,0] op_sel_hi:[0,1]
	v_lshlrev_b32_e32 v18, 16, v11
	v_and_b32_e32 v19, 0xffff0000, v11
	v_pk_fma_f32 v[14:15], v[28:29], v[32:33], v[14:15]
	v_lshlrev_b32_e32 v32, 16, v12
	v_pk_fma_f32 v[14:15], v[22:23], v[18:19], v[14:15] op_sel_hi:[0,1,1]
	v_pk_mul_f32 v[14:15], v[30:31], v[14:15] op_sel_hi:[0,1]
	v_lshlrev_b32_e32 v18, 16, v16
	v_and_b32_e32 v19, 0xffff0000, v20
	v_cvt_pk_bf16_f32 v11, v14, v15
	v_lshlrev_b32_e32 v14, 16, v20
	v_and_b32_e32 v15, 0xffff0000, v16
	v_pk_mul_f32 v[18:19], v[28:29], v[18:19] op_sel:[1,0] op_sel_hi:[0,1]
	v_and_b32_e32 v33, 0xffff0000, v12
	v_pk_fma_f32 v[14:15], v[28:29], v[14:15], v[18:19]
	v_lshlrev_b32_e32 v16, 16, v17
	v_pk_fma_f32 v[14:15], v[22:23], v[32:33], v[14:15] op_sel_hi:[0,1,1]
	v_pk_mul_f32 v[14:15], v[30:31], v[14:15] op_sel_hi:[0,1]
	v_cvt_pk_bf16_f32 v12, v14, v15
	v_and_b32_e32 v15, 0xffff0000, v17
	v_and_b32_e32 v17, 0xffff0000, v21
	v_lshlrev_b32_e32 v14, 16, v21
	v_pk_mul_f32 v[16:17], v[28:29], v[16:17] op_sel:[1,0] op_sel_hi:[0,1]
	v_pk_fma_f32 v[14:15], v[28:29], v[14:15], v[16:17]
	v_lshlrev_b32_e32 v16, 16, v13
	v_and_b32_e32 v17, 0xffff0000, v13
	v_pk_fma_f32 v[14:15], v[22:23], v[16:17], v[14:15] op_sel_hi:[0,1,1]
	v_pk_mul_f32 v[14:15], v[30:31], v[14:15] op_sel_hi:[0,1]
	v_cvt_pk_bf16_f32 v13, v14, v15
	v_lshlrev_b64 v[14:15], 12, v[26:27]
	v_lshl_add_u64 v[14:15], v[2:3], 0, v[14:15]
	global_store_dwordx4 v[14:15], v[10:13], off
	s_nop 1
	v_add_u32_e32 v10, 16, v115
	v_xor_b32_e32 v10, v10, v159
	v_lshlrev_b32_e32 v10, 4, v10
	v_and_b32_e32 v10, 0xf0, v10
	v_add3_u32 v10, s2, v10, v137
	ds_read_b64 v[22:23], v39 offset:128
	ds_read_b128 v[10:13], v10 offset:4096
	v_add_lshl_u32 v26, v6, 16, s79
	v_add_u32_e32 v26, s80, v26
	v_ashrrev_i32_e32 v27, 31, v26
	s_waitcnt vmcnt(16)
; #define LAS __attribute__((address_space(3)))
; __device__ __forceinline__ unsigned pk2(float lo, float hi) { f32x2 v = {lo, hi}; return __builtin_bit_cast(unsigned, __builtin_convertvector(v, bf16x2_t)); }
; __device__ __forceinline__ float bf_lo(unsigned w) { return __uint_as_float(w << 16); }
; __device__ __forceinline__ float bf_hi(unsigned w) { return __uint_as_float(w & 0xffff0000u); }
; template <int NA, int MG>
; __device__ __forceinline__ void attn_pair_unit(const Params& p, int l, int u, LAS unsigned char* pl, int sub, int lane, int& g, const bool own0, const int nu) {
;     ...
;           const int rr = 4 * t + qr2;
;           int qrow2;
;           if (!NA) qrow2 = b * SEQ + (((lq + rr) << dsh) + z); else qrow2 = b * SEQ + (iq - (r >> 4) + (rr >> 4)) * 64 + (cq - (r & 15)) + (rr & 15);
;           u32x4 v = *(const LAS u32x4*)(sg + rr * 256 + (((lane & 15) ^ (rr & 15)) * 16));
;           if (MG) {
;               const f32x2 m3 = *(const LAS f32x2*)(sg + 8192 + rr * 8);
;               const float* mlp = (const float*)(p.ws + OFF_ML);
;               const f32x2 ma = *(const f32x2*)(mlp + (((size_t)qrow2) * 8 + head) * 2), mb = *(const f32x2*)(mlp + (((size_t)MTOK + qrow2) * 8 + head) * 2);
;               const bf16_t* part = (const bf16_t*)(p.ws + OFF_PART);
;               const u32x4 oa = *(const u32x4*)(part + (size_t)qrow2 * 1024 + head * 128 + (lane & 15) * 8);
;               const u32x4 ob = *(const u32x4*)(part + ((size_t)MTOK + qrow2) * 1024 + head * 128 + (lane & 15) * 8);
;               const float mm = fmaxf(ma[0], fmaxf(mb[0], m3[0]));
;               const float wa = ma[1] * __builtin_amdgcn_exp2f(ma[0] - mm), wb = mb[1] * __builtin_amdgcn_exp2f(mb[0] - mm), w3 = m3[1] * __builtin_amdgcn_exp2f(m3[0] - mm);
;               const float winv = 1.0f / (wa + wb + w3);
; #pragma unroll
;               for (int e = 0; e < 4; ++e) {
;                   const float lo = (wa * bf_lo(oa[e]) + wb * bf_lo(ob[e]) + w3 * bf_lo(v[e])) * winv;
;                   const float hi = (wa * bf_hi(oa[e]) + wb * bf_hi(ob[e]) + w3 * bf_hi(v[e])) * winv;
;                   v[e] = pk2(lo, hi);
;               }
;           }
;           *(u32x4*)(dst + (size_t)qrow2 * dpitch + (lane & 15) * 8) = v;
	v_mov_b32_e32 v28, v88
	v_mov_b32_e32 v29, v89
	v_mov_b32_e32 v30, v90
	v_mov_b32_e32 v31, v91
	v_mov_b32_e32 v18, v96
	v_mov_b32_e32 v19, v97
	v_mov_b32_e32 v20, v98
	v_mov_b32_e32 v21, v99
	v_mov_b32_e32 v14, v92
	v_mov_b32_e32 v15, v93
	v_mov_b32_e32 v16, v94
	v_mov_b32_e32 v17, v95
	s_waitcnt lgkmcnt(0)
	v_lshlrev_b32_e32 v36, 16, v10
	v_and_b32_e32 v37, 0xffff0000, v10
	v_max3_f32 v34, v28, v30, v22
	v_sub_f32_e32 v28, v28, v34
	v_exp_f32_e32 v33, v28
	v_sub_f32_e32 v28, v30, v34
	v_exp_f32_e32 v32, v28
	v_sub_f32_e32 v22, v22, v34
	v_exp_f32_e32 v30, v22
	v_mov_b32_e32 v28, v31
	v_pk_mul_f32 v[28:29], v[28:29], v[32:33]
	v_and_b32_e32 v35, 0xffff0000, v18
	v_add_f32_e32 v31, v29, v28
	v_fmac_f32_e32 v31, v23, v30
	v_mul_f32_e32 v22, v23, v30
	v_div_scale_f32 v23, s[40:41], v31, v31, 1.0
	v_rcp_f32_e32 v30, v23
	s_nop 0
	v_fma_f32 v32, -v23, v30, 1.0
	v_fmac_f32_e32 v30, v32, v30
	v_div_scale_f32 v32, vcc, 1.0, v31, 1.0
	v_mul_f32_e32 v33, v32, v30
	v_fma_f32 v34, -v23, v33, v32
	v_fmac_f32_e32 v33, v34, v30
	v_fma_f32 v23, -v23, v33, v32
	v_lshlrev_b32_e32 v34, 16, v14
	v_div_fmas_f32 v23, v23, v30, v33
	v_lshlrev_b32_e32 v32, 16, v18
	v_and_b32_e32 v33, 0xffff0000, v14
	v_pk_mul_f32 v[34:35], v[28:29], v[34:35] op_sel:[1,0] op_sel_hi:[0,1]
	v_pk_fma_f32 v[32:33], v[28:29], v[32:33], v[34:35]
	v_div_fixup_f32 v30, v23, v31, 1.0
	v_pk_fma_f32 v[32:33], v[22:23], v[36:37], v[32:33] op_sel_hi:[0,1,1]
	v_pk_mul_f32 v[32:33], v[30:31], v[32:33] op_sel_hi:[0,1]
	v_cvt_pk_bf16_f32 v10, v32, v33
	v_and_b32_e32 v33, 0xffff0000, v15
	v_lshlrev_b32_e32 v14, 16, v15
	v_and_b32_e32 v15, 0xffff0000, v19
	v_lshlrev_b32_e32 v32, 16, v19
	v_pk_mul_f32 v[14:15], v[28:29], v[14:15] op_sel:[1,0] op_sel_hi:[0,1]
	v_lshlrev_b32_e32 v18, 16, v11
	v_and_b32_e32 v19, 0xffff0000, v11
	v_pk_fma_f32 v[14:15], v[28:29], v[32:33], v[14:15]
	v_lshlrev_b32_e32 v32, 16, v12
	v_pk_fma_f32 v[14:15], v[22:23], v[18:19], v[14:15] op_sel_hi:[0,1,1]
	v_pk_mul_f32 v[14:15], v[30:31], v[14:15] op_sel_hi:[0,1]
	v_lshlrev_b32_e32 v18, 16, v16
	v_and_b32_e32 v19, 0xffff0000, v20
	v_cvt_pk_bf16_f32 v11, v14, v15
	v_lshlrev_b32_e32 v14, 16, v20
	v_and_b32_e32 v15, 0xffff0000, v16
	v_pk_mul_f32 v[18:19], v[28:29], v[18:19] op_sel:[1,0] op_sel_hi:[0,1]
	v_and_b32_e32 v33, 0xffff0000, v12
	v_pk_fma_f32 v[14:15], v[28:29], v[14:15], v[18:19]
	v_lshlrev_b32_e32 v16, 16, v17
	v_pk_fma_f32 v[14:15], v[22:23], v[32:33], v[14:15] op_sel_hi:[0,1,1]
	v_pk_mul_f32 v[14:15], v[30:31], v[14:15] op_sel_hi:[0,1]
	v_cvt_pk_bf16_f32 v12, v14, v15
	v_and_b32_e32 v15, 0xffff0000, v17
	v_and_b32_e32 v17, 0xffff0000, v21
	v_lshlrev_b32_e32 v14, 16, v21
	v_pk_mul_f32 v[16:17], v[28:29], v[16:17] op_sel:[1,0] op_sel_hi:[0,1]
	v_pk_fma_f32 v[14:15], v[28:29], v[14:15], v[16:17]
	v_lshlrev_b32_e32 v16, 16, v13
	v_and_b32_e32 v17, 0xffff0000, v13
	v_pk_fma_f32 v[14:15], v[22:23], v[16:17], v[14:15] op_sel_hi:[0,1,1]
	v_pk_mul_f32 v[14:15], v[30:31], v[14:15] op_sel_hi:[0,1]
	v_cvt_pk_bf16_f32 v13, v14, v15
	v_lshlrev_b64 v[14:15], 12, v[26:27]
	v_lshl_add_u64 v[14:15], v[2:3], 0, v[14:15]
	global_store_dwordx4 v[14:15], v[10:13], off
	s_nop 1
	v_add_u32_e32 v10, 20, v115
	v_xor_b32_e32 v10, v10, v159
	v_lshlrev_b32_e32 v10, 4, v10
	v_and_b32_e32 v10, 0xf0, v10
	v_add3_u32 v10, s2, v10, v137
	ds_read_b64 v[22:23], v39 offset:160
	ds_read_b128 v[10:13], v10 offset:5120
	v_add_lshl_u32 v26, v6, 20, s79
	v_add_u32_e32 v26, s80, v26
	v_ashrrev_i32_e32 v27, 31, v26
	s_waitcnt vmcnt(13)
	v_mov_b32_e32 v28, v100
	v_mov_b32_e32 v29, v101
	v_mov_b32_e32 v30, v102
	v_mov_b32_e32 v31, v103
	v_mov_b32_e32 v18, v108
	v_mov_b32_e32 v19, v109
	v_mov_b32_e32 v20, v110
	v_mov_b32_e32 v21, v111
	v_mov_b32_e32 v14, v104
	v_mov_b32_e32 v15, v105
	v_mov_b32_e32 v16, v106
	v_mov_b32_e32 v17, v107
	s_waitcnt lgkmcnt(0)
	v_lshlrev_b32_e32 v36, 16, v10
	v_and_b32_e32 v37, 0xffff0000, v10
	v_max3_f32 v34, v28, v30, v22
	v_sub_f32_e32 v28, v28, v34
	v_exp_f32_e32 v33, v28
	v_sub_f32_e32 v28, v30, v34
	v_exp_f32_e32 v32, v28
	v_sub_f32_e32 v22, v22, v34
	v_exp_f32_e32 v30, v22
	v_mov_b32_e32 v28, v31
	v_pk_mul_f32 v[28:29], v[28:29], v[32:33]
	v_and_b32_e32 v35, 0xffff0000, v18
	v_add_f32_e32 v31, v29, v28
	v_fmac_f32_e32 v31, v23, v30
	v_mul_f32_e32 v22, v23, v30
	v_div_scale_f32 v23, s[40:41], v31, v31, 1.0
	v_rcp_f32_e32 v30, v23
	s_nop 0
	v_fma_f32 v32, -v23, v30, 1.0
	v_fmac_f32_e32 v30, v32, v30
	v_div_scale_f32 v32, vcc, 1.0, v31, 1.0
	v_mul_f32_e32 v33, v32, v30
	v_fma_f32 v34, -v23, v33, v32
	v_fmac_f32_e32 v33, v34, v30
	v_fma_f32 v23, -v23, v33, v32
	v_lshlrev_b32_e32 v34, 16, v14
	v_div_fmas_f32 v23, v23, v30, v33
	v_lshlrev_b32_e32 v32, 16, v18
	v_and_b32_e32 v33, 0xffff0000, v14
	v_pk_mul_f32 v[34:35], v[28:29], v[34:35] op_sel:[1,0] op_sel_hi:[0,1]
	v_pk_fma_f32 v[32:33], v[28:29], v[32:33], v[34:35]
	v_div_fixup_f32 v30, v23, v31, 1.0
	v_pk_fma_f32 v[32:33], v[22:23], v[36:37], v[32:33] op_sel_hi:[0,1,1]
	v_pk_mul_f32 v[32:33], v[30:31], v[32:33] op_sel_hi:[0,1]
	v_cvt_pk_bf16_f32 v10, v32, v33
	v_and_b32_e32 v33, 0xffff0000, v15
	v_lshlrev_b32_e32 v14, 16, v15
	v_and_b32_e32 v15, 0xffff0000, v19
	v_lshlrev_b32_e32 v32, 16, v19
	v_pk_mul_f32 v[14:15], v[28:29], v[14:15] op_sel:[1,0] op_sel_hi:[0,1]
	v_lshlrev_b32_e32 v18, 16, v11
	v_and_b32_e32 v19, 0xffff0000, v11
	v_pk_fma_f32 v[14:15], v[28:29], v[32:33], v[14:15]
	v_lshlrev_b32_e32 v32, 16, v12
	v_pk_fma_f32 v[14:15], v[22:23], v[18:19], v[14:15] op_sel_hi:[0,1,1]
	v_pk_mul_f32 v[14:15], v[30:31], v[14:15] op_sel_hi:[0,1]
	v_lshlrev_b32_e32 v18, 16, v16
	v_and_b32_e32 v19, 0xffff0000, v20
	v_cvt_pk_bf16_f32 v11, v14, v15
	v_lshlrev_b32_e32 v14, 16, v20
	v_and_b32_e32 v15, 0xffff0000, v16
	v_pk_mul_f32 v[18:19], v[28:29], v[18:19] op_sel:[1,0] op_sel_hi:[0,1]
	v_and_b32_e32 v33, 0xffff0000, v12
	v_pk_fma_f32 v[14:15], v[28:29], v[14:15], v[18:19]
	v_lshlrev_b32_e32 v16, 16, v17
	v_pk_fma_f32 v[14:15], v[22:23], v[32:33], v[14:15] op_sel_hi:[0,1,1]
	v_pk_mul_f32 v[14:15], v[30:31], v[14:15] op_sel_hi:[0,1]
	v_cvt_pk_bf16_f32 v12, v14, v15
	v_and_b32_e32 v15, 0xffff0000, v17
	v_and_b32_e32 v17, 0xffff0000, v21
	v_lshlrev_b32_e32 v14, 16, v21
	v_pk_mul_f32 v[16:17], v[28:29], v[16:17] op_sel:[1,0] op_sel_hi:[0,1]
	v_pk_fma_f32 v[14:15], v[28:29], v[14:15], v[16:17]
	v_lshlrev_b32_e32 v16, 16, v13
	v_and_b32_e32 v17, 0xffff0000, v13
	v_pk_fma_f32 v[14:15], v[22:23], v[16:17], v[14:15] op_sel_hi:[0,1,1]
	v_pk_mul_f32 v[14:15], v[30:31], v[14:15] op_sel_hi:[0,1]
	v_cvt_pk_bf16_f32 v13, v14, v15
	v_lshlrev_b64 v[14:15], 12, v[26:27]
	v_lshl_add_u64 v[14:15], v[2:3], 0, v[14:15]
	global_store_dwordx4 v[14:15], v[10:13], off
	s_nop 1
	v_add_u32_e32 v10, 24, v115
	v_xor_b32_e32 v10, v10, v159
	v_lshlrev_b32_e32 v10, 4, v10
	v_and_b32_e32 v10, 0xf0, v10
	v_add3_u32 v10, s2, v10, v137
	ds_read_b64 v[22:23], v39 offset:192
	ds_read_b128 v[10:13], v10 offset:6144
	v_add_lshl_u32 v26, v6, 24, s79
	v_add_u32_e32 v26, s80, v26
	v_ashrrev_i32_e32 v27, 31, v26
	s_waitcnt vmcnt(10)
; #define LAS __attribute__((address_space(3)))
; __device__ __forceinline__ unsigned pk2(float lo, float hi) { f32x2 v = {lo, hi}; return __builtin_bit_cast(unsigned, __builtin_convertvector(v, bf16x2_t)); }
; __device__ __forceinline__ float bf_lo(unsigned w) { return __uint_as_float(w << 16); }
; __device__ __forceinline__ float bf_hi(unsigned w) { return __uint_as_float(w & 0xffff0000u); }
; template <int NA, int MG>
; __device__ __forceinline__ void attn_pair_unit(const Params& p, int l, int u, LAS unsigned char* pl, int sub, int lane, int& g, const bool own0, const int nu) {
;     ...
;           const int rr = 4 * t + qr2;
;           int qrow2;
;           if (!NA) qrow2 = b * SEQ + (((lq + rr) << dsh) + z); else qrow2 = b * SEQ + (iq - (r >> 4) + (rr >> 4)) * 64 + (cq - (r & 15)) + (rr & 15);
;           u32x4 v = *(const LAS u32x4*)(sg + rr * 256 + (((lane & 15) ^ (rr & 15)) * 16));
;           if (MG) {
;               const f32x2 m3 = *(const LAS f32x2*)(sg + 8192 + rr * 8);
;               const float* mlp = (const float*)(p.ws + OFF_ML);
;               const f32x2 ma = *(const f32x2*)(mlp + (((size_t)qrow2) * 8 + head) * 2), mb = *(const f32x2*)(mlp + (((size_t)MTOK + qrow2) * 8 + head) * 2);
;               const bf16_t* part = (const bf16_t*)(p.ws + OFF_PART);
;               const u32x4 oa = *(const u32x4*)(part + (size_t)qrow2 * 1024 + head * 128 + (lane & 15) * 8);
;               const u32x4 ob = *(const u32x4*)(part + ((size_t)MTOK + qrow2) * 1024 + head * 128 + (lane & 15) * 8);
;               const float mm = fmaxf(ma[0], fmaxf(mb[0], m3[0]));
;               const float wa = ma[1] * __builtin_amdgcn_exp2f(ma[0] - mm), wb = mb[1] * __builtin_amdgcn_exp2f(mb[0] - mm), w3 = m3[1] * __builtin_amdgcn_exp2f(m3[0] - mm);
;               const float winv = 1.0f / (wa + wb + w3);
; #pragma unroll
;               for (int e = 0; e < 4; ++e) {
;                   const float lo = (wa * bf_lo(oa[e]) + wb * bf_lo(ob[e]) + w3 * bf_lo(v[e])) * winv;
;                   const float hi = (wa * bf_hi(oa[e]) + wb * bf_hi(ob[e]) + w3 * bf_hi(v[e])) * winv;
;                   v[e] = pk2(lo, hi);
;               }
;           }
;           *(u32x4*)(dst + (size_t)qrow2 * dpitch + (lane & 15) * 8) = v;
	v_mov_b32_e32 v28, v184
	v_mov_b32_e32 v29, v185
	v_mov_b32_e32 v30, v186
	v_mov_b32_e32 v31, v187
	v_mov_b32_e32 v18, v192
	v_mov_b32_e32 v19, v193
	v_mov_b32_e32 v20, v194
	v_mov_b32_e32 v21, v195
	v_mov_b32_e32 v14, v188
	v_mov_b32_e32 v15, v189
	v_mov_b32_e32 v16, v190
	v_mov_b32_e32 v17, v191
	s_waitcnt lgkmcnt(0)
	v_lshlrev_b32_e32 v36, 16, v10
	v_and_b32_e32 v37, 0xffff0000, v10
	v_max3_f32 v34, v28, v30, v22
	v_sub_f32_e32 v28, v28, v34
	v_exp_f32_e32 v33, v28
	v_sub_f32_e32 v28, v30, v34
	v_exp_f32_e32 v32, v28
	v_sub_f32_e32 v22, v22, v34
	v_exp_f32_e32 v30, v22
	v_mov_b32_e32 v28, v31
	v_pk_mul_f32 v[28:29], v[28:29], v[32:33]
	v_and_b32_e32 v35, 0xffff0000, v18
	v_add_f32_e32 v31, v29, v28
	v_fmac_f32_e32 v31, v23, v30
	v_mul_f32_e32 v22, v23, v30
	v_div_scale_f32 v23, s[40:41], v31, v31, 1.0
	v_rcp_f32_e32 v30, v23
	s_nop 0
	v_fma_f32 v32, -v23, v30, 1.0
	v_fmac_f32_e32 v30, v32, v30
	v_div_scale_f32 v32, vcc, 1.0, v31, 1.0
	v_mul_f32_e32 v33, v32, v30
	v_fma_f32 v34, -v23, v33, v32
	v_fmac_f32_e32 v33, v34, v30
	v_fma_f32 v23, -v23, v33, v32
	v_lshlrev_b32_e32 v34, 16, v14
	v_div_fmas_f32 v23, v23, v30, v33
	v_lshlrev_b32_e32 v32, 16, v18
	v_and_b32_e32 v33, 0xffff0000, v14
	v_pk_mul_f32 v[34:35], v[28:29], v[34:35] op_sel:[1,0] op_sel_hi:[0,1]
	v_pk_fma_f32 v[32:33], v[28:29], v[32:33], v[34:35]
	v_div_fixup_f32 v30, v23, v31, 1.0
	v_pk_fma_f32 v[32:33], v[22:23], v[36:37], v[32:33] op_sel_hi:[0,1,1]
	v_pk_mul_f32 v[32:33], v[30:31], v[32:33] op_sel_hi:[0,1]
	v_cvt_pk_bf16_f32 v10, v32, v33
	v_and_b32_e32 v33, 0xffff0000, v15
	v_lshlrev_b32_e32 v14, 16, v15
	v_and_b32_e32 v15, 0xffff0000, v19
	v_lshlrev_b32_e32 v32, 16, v19
	v_pk_mul_f32 v[14:15], v[28:29], v[14:15] op_sel:[1,0] op_sel_hi:[0,1]
	v_lshlrev_b32_e32 v18, 16, v11
	v_and_b32_e32 v19, 0xffff0000, v11
	v_pk_fma_f32 v[14:15], v[28:29], v[32:33], v[14:15]
	v_lshlrev_b32_e32 v32, 16, v12
	v_pk_fma_f32 v[14:15], v[22:23], v[18:19], v[14:15] op_sel_hi:[0,1,1]
	v_pk_mul_f32 v[14:15], v[30:31], v[14:15] op_sel_hi:[0,1]
	v_lshlrev_b32_e32 v18, 16, v16
	v_and_b32_e32 v19, 0xffff0000, v20
	v_cvt_pk_bf16_f32 v11, v14, v15
	v_lshlrev_b32_e32 v14, 16, v20
	v_and_b32_e32 v15, 0xffff0000, v16
	v_pk_mul_f32 v[18:19], v[28:29], v[18:19] op_sel:[1,0] op_sel_hi:[0,1]
	v_and_b32_e32 v33, 0xffff0000, v12
	v_pk_fma_f32 v[14:15], v[28:29], v[14:15], v[18:19]
	v_lshlrev_b32_e32 v16, 16, v17
	v_pk_fma_f32 v[14:15], v[22:23], v[32:33], v[14:15] op_sel_hi:[0,1,1]
	v_pk_mul_f32 v[14:15], v[30:31], v[14:15] op_sel_hi:[0,1]
	v_cvt_pk_bf16_f32 v12, v14, v15
	v_and_b32_e32 v15, 0xffff0000, v17
	v_and_b32_e32 v17, 0xffff0000, v21
	v_lshlrev_b32_e32 v14, 16, v21
	v_pk_mul_f32 v[16:17], v[28:29], v[16:17] op_sel:[1,0] op_sel_hi:[0,1]
	v_pk_fma_f32 v[14:15], v[28:29], v[14:15], v[16:17]
	v_lshlrev_b32_e32 v16, 16, v13
	v_and_b32_e32 v17, 0xffff0000, v13
	v_pk_fma_f32 v[14:15], v[22:23], v[16:17], v[14:15] op_sel_hi:[0,1,1]
	v_pk_mul_f32 v[14:15], v[30:31], v[14:15] op_sel_hi:[0,1]
	v_cvt_pk_bf16_f32 v13, v14, v15
	v_lshlrev_b64 v[14:15], 12, v[26:27]
	v_lshl_add_u64 v[14:15], v[2:3], 0, v[14:15]
	global_store_dwordx4 v[14:15], v[10:13], off
	s_nop 1
	v_add_u32_e32 v10, 28, v115
	v_xor_b32_e32 v10, v10, v159
	v_lshlrev_b32_e32 v10, 4, v10
	v_and_b32_e32 v10, 0xf0, v10
	v_add3_u32 v10, s2, v10, v137
	ds_read_b64 v[22:23], v39 offset:224
	ds_read_b128 v[10:13], v10 offset:7168
	v_add_lshl_u32 v26, v6, 28, s79
	v_add_u32_e32 v26, s80, v26
	v_ashrrev_i32_e32 v27, 31, v26
	s_waitcnt vmcnt(7)
	v_mov_b32_e32 v28, v140
	v_mov_b32_e32 v29, v141
	v_mov_b32_e32 v30, v142
	v_mov_b32_e32 v31, v143
	v_mov_b32_e32 v18, v214
	v_mov_b32_e32 v19, v215
	v_mov_b32_e32 v20, v216
	v_mov_b32_e32 v21, v217
	v_mov_b32_e32 v14, v210
	v_mov_b32_e32 v15, v211
	v_mov_b32_e32 v16, v212
	v_mov_b32_e32 v17, v213
	s_waitcnt lgkmcnt(0)
	v_lshlrev_b32_e32 v36, 16, v10
	v_and_b32_e32 v37, 0xffff0000, v10
	v_max3_f32 v34, v28, v30, v22
	v_sub_f32_e32 v28, v28, v34
	v_exp_f32_e32 v33, v28
	v_sub_f32_e32 v28, v30, v34
	v_exp_f32_e32 v32, v28
	v_sub_f32_e32 v22, v22, v34
	v_exp_f32_e32 v30, v22
	v_mov_b32_e32 v28, v31
	v_pk_mul_f32 v[28:29], v[28:29], v[32:33]
	v_and_b32_e32 v35, 0xffff0000, v18
	v_add_f32_e32 v31, v29, v28
	v_fmac_f32_e32 v31, v23, v30
	v_mul_f32_e32 v22, v23, v30
	v_div_scale_f32 v23, s[40:41], v31, v31, 1.0
	v_rcp_f32_e32 v30, v23
	s_nop 0
	v_fma_f32 v32, -v23, v30, 1.0
	v_fmac_f32_e32 v30, v32, v30
	v_div_scale_f32 v32, vcc, 1.0, v31, 1.0
	v_mul_f32_e32 v33, v32, v30
	v_fma_f32 v34, -v23, v33, v32
	v_fmac_f32_e32 v33, v34, v30
	v_fma_f32 v23, -v23, v33, v32
	v_lshlrev_b32_e32 v34, 16, v14
	v_div_fmas_f32 v23, v23, v30, v33
	v_lshlrev_b32_e32 v32, 16, v18
	v_and_b32_e32 v33, 0xffff0000, v14
	v_pk_mul_f32 v[34:35], v[28:29], v[34:35] op_sel:[1,0] op_sel_hi:[0,1]
	v_pk_fma_f32 v[32:33], v[28:29], v[32:33], v[34:35]
	v_div_fixup_f32 v30, v23, v31, 1.0
	v_pk_fma_f32 v[32:33], v[22:23], v[36:37], v[32:33] op_sel_hi:[0,1,1]
	v_pk_mul_f32 v[32:33], v[30:31], v[32:33] op_sel_hi:[0,1]
	v_cvt_pk_bf16_f32 v10, v32, v33
	v_and_b32_e32 v33, 0xffff0000, v15
	v_lshlrev_b32_e32 v14, 16, v15
	v_and_b32_e32 v15, 0xffff0000, v19
	v_lshlrev_b32_e32 v32, 16, v19
	v_pk_mul_f32 v[14:15], v[28:29], v[14:15] op_sel:[1,0] op_sel_hi:[0,1]
	v_lshlrev_b32_e32 v18, 16, v11
	v_and_b32_e32 v19, 0xffff0000, v11
	v_pk_fma_f32 v[14:15], v[28:29], v[32:33], v[14:15]
	v_lshlrev_b32_e32 v32, 16, v12
	v_pk_fma_f32 v[14:15], v[22:23], v[18:19], v[14:15] op_sel_hi:[0,1,1]
	v_pk_mul_f32 v[14:15], v[30:31], v[14:15] op_sel_hi:[0,1]
	v_lshlrev_b32_e32 v18, 16, v16
	v_and_b32_e32 v19, 0xffff0000, v20
	v_cvt_pk_bf16_f32 v11, v14, v15
	v_lshlrev_b32_e32 v14, 16, v20
	v_and_b32_e32 v15, 0xffff0000, v16
	v_pk_mul_f32 v[18:19], v[28:29], v[18:19] op_sel:[1,0] op_sel_hi:[0,1]
	v_and_b32_e32 v33, 0xffff0000, v12
	v_pk_fma_f32 v[14:15], v[28:29], v[14:15], v[18:19]
	v_lshlrev_b32_e32 v16, 16, v17
	v_pk_fma_f32 v[14:15], v[22:23], v[32:33], v[14:15] op_sel_hi:[0,1,1]
	v_pk_mul_f32 v[14:15], v[30:31], v[14:15] op_sel_hi:[0,1]
	v_cvt_pk_bf16_f32 v12, v14, v15
	v_and_b32_e32 v15, 0xffff0000, v17
	v_and_b32_e32 v17, 0xffff0000, v21
	v_lshlrev_b32_e32 v14, 16, v21
	v_pk_mul_f32 v[16:17], v[28:29], v[16:17] op_sel:[1,0] op_sel_hi:[0,1]
	v_pk_fma_f32 v[14:15], v[28:29], v[14:15], v[16:17]
	v_lshlrev_b32_e32 v16, 16, v13
	v_and_b32_e32 v17, 0xffff0000, v13
	v_pk_fma_f32 v[14:15], v[22:23], v[16:17], v[14:15] op_sel_hi:[0,1,1]
	v_pk_mul_f32 v[14:15], v[30:31], v[14:15] op_sel_hi:[0,1]
	v_cvt_pk_bf16_f32 v13, v14, v15
	v_lshlrev_b64 v[14:15], 12, v[26:27]
	v_lshl_add_u64 v[14:15], v[2:3], 0, v[14:15]
	global_store_dwordx4 v[14:15], v[10:13], off
	s_nop 1
	s_waitcnt lgkmcnt(0)
	s_add_i32 s93, s93, 2
	s_add_i32 s75, s75, 1
	s_cmp_eq_u32 s75, 4
	s_cbranch_scc0 .LBB0_151
; #define LAS __attribute__((address_space(3)))
; #define LDS_WAIT() asm volatile("s_waitcnt lgkmcnt(0)" ::: "memory")
; __device__ __forceinline__ void phase_attn(const Params& p, int l, int stage, LAS unsigned char* lds, const int tid, const int bid) {
;     ...
;           LAS float* bl = (LAS float*)(pl + 4 * VTILE); const float* rb = p.rpb + ((size_t)l * 8 + x) * 465;
;           for (int i = lane; i < 465; i += 64) bl[i] = rb[i] * 1.4426950408889634f; LDS_WAIT(); }
	v_readlane_b32 s2, v254, 17
	s_lshl_b32 s2, s2, 3
	s_or_b32 s2, s2, s71
	s_mul_hi_i32 s3, s2, 0x744
	s_mulk_i32 s2, 0x744
	s_add_u32 s2, s42, s2
	s_addc_u32 s3, s43, s3
	v_lshlrev_b32_e32 v2, 2, v159
	global_load_dword v3, v2, s[2:3]
	global_load_dword v5, v2, s[2:3] offset:256
	v_add_u32_e32 v4, s67, v2
	s_movk_i32 s4, 0x191
	s_waitcnt vmcnt(1)
	v_mul_f32_e32 v3, 0x3fb8aa3b, v3
	s_waitcnt vmcnt(0)
	v_mul_f32_e32 v5, 0x3fb8aa3b, v5
	ds_write2st64_b32 v4, v3, v5 offset0:132 offset1:133
	global_load_dword v3, v2, s[2:3] offset:512
	global_load_dword v5, v2, s[2:3] offset:768
	s_waitcnt vmcnt(1)
	v_mul_f32_e32 v3, 0x3fb8aa3b, v3
	s_waitcnt vmcnt(0)
	v_mul_f32_e32 v5, 0x3fb8aa3b, v5
	ds_write2st64_b32 v4, v3, v5 offset0:134 offset1:135
	global_load_dword v3, v2, s[2:3] offset:1024
	global_load_dword v5, v2, s[2:3] offset:1280
	s_waitcnt vmcnt(1)
	v_mul_f32_e32 v3, 0x3fb8aa3b, v3
	s_waitcnt vmcnt(0)
	v_mul_f32_e32 v5, 0x3fb8aa3b, v5
	ds_write2st64_b32 v4, v3, v5 offset0:136 offset1:137
	global_load_dword v5, v2, s[2:3] offset:1536
	v_or_b32_e32 v3, 0x180, v159
	v_cmp_gt_u32_e32 vcc, s4, v3
	s_waitcnt vmcnt(0)
	v_mul_f32_e32 v5, 0x3fb8aa3b, v5
	ds_write_b32 v4, v5 offset:35328
	s_and_saveexec_b64 s[4:5], vcc
	s_cbranch_execz .LBB0_176
	v_mov_b32_e32 v3, v1
	v_lshl_add_u64 v[2:3], s[2:3], 0, v[2:3]
	global_load_dword v2, v[2:3], off offset:1792
	s_waitcnt vmcnt(0)
	v_mul_f32_e32 v2, 0x3fb8aa3b, v2
	ds_write_b32 v4, v2 offset:35584
